# scheduler resume (in-proj, ffn-up) + prep MOD loop blocked x4 (32 weight loads in flight) + norm2 x-load hoist
# speedup vs baseline: 1.0056x; 1.0044x over previous
.LBB0_1340:
	v_lshl_add_u64 v[100:101], v[98:99], 0, s[62:63]
	v_add_co_u32_e64 v116, s[58:59], s24, v100
	s_mov_b32 s0, 0x1e000
	s_nop 0
	v_addc_co_u32_e64 v117, s[58:59], 0, v101, s[58:59]
	v_add_co_u32_e64 v118, s[58:59], s0, v100
	s_mov_b32 s0, 0x2a000
	s_nop 0
	v_addc_co_u32_e64 v119, s[58:59], 0, v101, s[58:59]
	v_add_co_u32_e64 v120, s[58:59], s23, v100
	v_add_co_u32_e32 v114, vcc, 0x6000, v100
	s_nop 0
	v_addc_co_u32_e64 v121, s[58:59], 0, v101, s[58:59]
	v_add_co_u32_e64 v122, s[58:59], s0, v100
	s_nop 1
	v_addc_co_u32_e64 v123, s[58:59], 0, v101, s[58:59]
	s_mov_b64 s[58:59], vcc
	v_add_co_u32_e32 v124, vcc, 0xc000, v100
	v_addc_co_u32_e64 v115, s[58:59], 0, v101, s[58:59]
	global_load_dword v112, v[100:101], off
	s_nop 0
	global_load_dword v118, v[118:119], off
	s_nop 0
	global_load_dword v116, v[116:117], off
	s_nop 0
	global_load_dword v120, v[120:121], off
	s_nop 0
	global_load_dword v122, v[122:123], off
	s_nop 0
	global_load_dword v114, v[114:115], off
	s_mov_b64 s[58:59], vcc
	v_add_co_u32_e32 v100, vcc, s97, v100
	v_addc_co_u32_e64 v125, s[58:59], 0, v101, s[58:59]
	s_nop 0
	v_addc_co_u32_e32 v101, vcc, 0, v101, vcc
	global_load_dword v124, v[124:125], off
	global_load_dword v100, v[100:101], off
	s_add_u32 s100, s62, 0x30000
	s_addc_u32 s101, s63, 0
	v_lshl_add_u64 v[142:143], v[98:99], 0, s[100:101]
	v_add_co_u32_e64 v132, s[58:59], s24, v142
	s_mov_b32 s0, 0x1e000
	s_nop 0
	v_addc_co_u32_e64 v133, s[58:59], 0, v143, s[58:59]
	v_add_co_u32_e64 v134, s[58:59], s0, v142
	s_mov_b32 s0, 0x2a000
	s_nop 0
	v_addc_co_u32_e64 v135, s[58:59], 0, v143, s[58:59]
	v_add_co_u32_e64 v136, s[58:59], s23, v142
	v_add_co_u32_e32 v130, vcc, 0x6000, v142
	s_nop 0
	v_addc_co_u32_e64 v137, s[58:59], 0, v143, s[58:59]
	v_add_co_u32_e64 v138, s[58:59], s0, v142
	s_nop 1
	v_addc_co_u32_e64 v139, s[58:59], 0, v143, s[58:59]
	s_mov_b64 s[58:59], vcc
	v_add_co_u32_e32 v140, vcc, 0xc000, v142
	v_addc_co_u32_e64 v131, s[58:59], 0, v143, s[58:59]
	global_load_dword v128, v[142:143], off
	s_nop 0
	global_load_dword v134, v[134:135], off
	s_nop 0
	global_load_dword v132, v[132:133], off
	s_nop 0
	global_load_dword v136, v[136:137], off
	s_nop 0
	global_load_dword v138, v[138:139], off
	s_nop 0
	global_load_dword v130, v[130:131], off
	s_mov_b64 s[58:59], vcc
	v_add_co_u32_e32 v142, vcc, s97, v142
	v_addc_co_u32_e64 v141, s[58:59], 0, v143, s[58:59]
	s_nop 0
	v_addc_co_u32_e32 v143, vcc, 0, v143, vcc
	global_load_dword v140, v[140:141], off
	global_load_dword v142, v[142:143], off
	s_add_u32 s100, s62, 0x60000
	s_addc_u32 s101, s63, 0
	v_lshl_add_u64 v[158:159], v[98:99], 0, s[100:101]
	v_add_co_u32_e64 v148, s[58:59], s24, v158
	s_mov_b32 s0, 0x1e000
	s_nop 0
	v_addc_co_u32_e64 v149, s[58:59], 0, v159, s[58:59]
	v_add_co_u32_e64 v150, s[58:59], s0, v158
	s_mov_b32 s0, 0x2a000
	s_nop 0
	v_addc_co_u32_e64 v151, s[58:59], 0, v159, s[58:59]
	v_add_co_u32_e64 v152, s[58:59], s23, v158
	v_add_co_u32_e32 v146, vcc, 0x6000, v158
	s_nop 0
	v_addc_co_u32_e64 v153, s[58:59], 0, v159, s[58:59]
	v_add_co_u32_e64 v154, s[58:59], s0, v158
	s_nop 1
	v_addc_co_u32_e64 v155, s[58:59], 0, v159, s[58:59]
	s_mov_b64 s[58:59], vcc
	v_add_co_u32_e32 v156, vcc, 0xc000, v158
	v_addc_co_u32_e64 v147, s[58:59], 0, v159, s[58:59]
	global_load_dword v144, v[158:159], off
	s_nop 0
	global_load_dword v150, v[150:151], off
	s_nop 0
	global_load_dword v148, v[148:149], off
	s_nop 0
	global_load_dword v152, v[152:153], off
	s_nop 0
	global_load_dword v154, v[154:155], off
	s_nop 0
	global_load_dword v146, v[146:147], off
	s_mov_b64 s[58:59], vcc
	v_add_co_u32_e32 v158, vcc, s97, v158
	v_addc_co_u32_e64 v157, s[58:59], 0, v159, s[58:59]
	s_nop 0
	v_addc_co_u32_e32 v159, vcc, 0, v159, vcc
	global_load_dword v156, v[156:157], off
	global_load_dword v158, v[158:159], off
	s_add_u32 s100, s62, 0x90000
	s_addc_u32 s101, s63, 0
	v_lshl_add_u64 v[174:175], v[98:99], 0, s[100:101]
	v_add_co_u32_e64 v164, s[58:59], s24, v174
	s_mov_b32 s0, 0x1e000
	s_nop 0
	v_addc_co_u32_e64 v165, s[58:59], 0, v175, s[58:59]
	v_add_co_u32_e64 v166, s[58:59], s0, v174
	s_mov_b32 s0, 0x2a000
	s_nop 0
	v_addc_co_u32_e64 v167, s[58:59], 0, v175, s[58:59]
	v_add_co_u32_e64 v168, s[58:59], s23, v174
	v_add_co_u32_e32 v162, vcc, 0x6000, v174
	s_nop 0
	v_addc_co_u32_e64 v169, s[58:59], 0, v175, s[58:59]
	v_add_co_u32_e64 v170, s[58:59], s0, v174
	s_nop 1
	v_addc_co_u32_e64 v171, s[58:59], 0, v175, s[58:59]
	s_mov_b64 s[58:59], vcc
	v_add_co_u32_e32 v172, vcc, 0xc000, v174
	v_addc_co_u32_e64 v163, s[58:59], 0, v175, s[58:59]
	global_load_dword v160, v[174:175], off
	s_nop 0
	global_load_dword v166, v[166:167], off
	s_nop 0
	global_load_dword v164, v[164:165], off
	s_nop 0
	global_load_dword v168, v[168:169], off
	s_nop 0
	global_load_dword v170, v[170:171], off
	s_nop 0
	global_load_dword v162, v[162:163], off
	s_mov_b64 s[58:59], vcc
	v_add_co_u32_e32 v174, vcc, s97, v174
	v_addc_co_u32_e64 v173, s[58:59], 0, v175, s[58:59]
	s_nop 0
	v_addc_co_u32_e32 v175, vcc, 0, v175, vcc
	global_load_dword v172, v[172:173], off
	global_load_dword v174, v[174:175], off
	ds_read_b128 v[8:11], v106
	ds_read_b128 v[4:7], v106 offset:16
	ds_read_b128 v[0:3], v106 offset:4096
	ds_read_b128 v[12:15], v106 offset:4112
	ds_read_b128 v[28:31], v106 offset:8192
	ds_read_b128 v[36:39], v106 offset:8208
	ds_read_b128 v[16:19], v106 offset:12288
	ds_read_b128 v[20:23], v106 offset:12304
	ds_read_b128 v[40:43], v106 offset:16384
	ds_read_b128 v[44:47], v106 offset:16400
	ds_read_b128 v[24:27], v106 offset:20480
	ds_read_b128 v[32:35], v106 offset:20496
	ds_read_b128 v[60:63], v106 offset:24576
	ds_read_b128 v[64:67], v106 offset:24592
	ds_read_b128 v[48:51], v106 offset:28672
	ds_read_b128 v[56:59], v106 offset:28688
	ds_read_b128 v[52:55], v106 offset:32768
	ds_read_b128 v[108:111], v106 offset:32784
	s_waitcnt lgkmcnt(14)
	v_mov_b32_e32 v127, v0
	v_mov_b32_e32 v0, v9
	v_mov_b32_e32 v9, v2
	v_mov_b32_e32 v2, v11
	s_waitcnt lgkmcnt(11)
	v_mov_b32_e32 v11, v16
	v_mov_b32_e32 v16, v29
	v_mov_b32_e32 v29, v18
	v_mov_b32_e32 v18, v31
	s_waitcnt lgkmcnt(7)
	v_mov_b32_e32 v31, v24
	v_mov_b32_e32 v24, v41
	v_mov_b32_e32 v41, v26
	v_mov_b32_e32 v26, v43
	s_waitcnt lgkmcnt(3)
	v_mov_b32_e32 v43, v48
	v_mov_b32_e32 v48, v61
	v_mov_b32_e32 v126, v8
	v_mov_b32_e32 v8, v10
	v_mov_b32_e32 v10, v28
	v_mov_b32_e32 v28, v30
	v_mov_b32_e32 v30, v40
	v_mov_b32_e32 v40, v42
	v_mov_b32_e32 v42, v60
	v_mov_b32_e32 v61, v50
	v_mov_b32_e32 v50, v63
	v_mov_b32_e32 v63, v12
	v_mov_b32_e32 v12, v5
	v_mov_b32_e32 v5, v14
	v_mov_b32_e32 v14, v7
	v_mov_b32_e32 v7, v20
	v_mov_b32_e32 v20, v37
	v_mov_b32_e32 v37, v22
	v_mov_b32_e32 v22, v39
	v_mov_b32_e32 v39, v32
	v_mov_b32_e32 v32, v45
	v_mov_b32_e32 v45, v34
	v_mov_b32_e32 v34, v47
	s_waitcnt lgkmcnt(2)
	v_mov_b32_e32 v47, v56
	v_mov_b32_e32 v56, v65
	v_mov_b32_e32 v60, v62
	v_mov_b32_e32 v62, v4
	v_mov_b32_e32 v4, v6
	v_mov_b32_e32 v6, v36
	v_mov_b32_e32 v36, v38
	v_mov_b32_e32 v38, v44
	v_mov_b32_e32 v44, v46
	v_mov_b32_e32 v46, v64
	v_mov_b32_e32 v64, v66
	v_mov_b32_e32 v65, v58
	v_mov_b32_e32 v58, v67
	s_waitcnt vmcnt(30)
	v_pk_mul_f32 v[12:13], v[118:119], v[12:13] op_sel_hi:[0,1]
	v_pk_mul_f32 v[20:21], v[118:119], v[20:21] op_sel_hi:[0,1]
	v_pk_mul_f32 v[32:33], v[118:119], v[32:33] op_sel_hi:[0,1]
	v_pk_mul_f32 v[56:57], v[118:119], v[56:57] op_sel_hi:[0,1]
	s_waitcnt vmcnt(26)
	v_pk_mul_f32 v[0:1], v[114:115], v[0:1] op_sel_hi:[0,1]
	v_pk_mul_f32 v[16:17], v[114:115], v[16:17] op_sel_hi:[0,1]
	v_pk_mul_f32 v[24:25], v[114:115], v[24:25] op_sel_hi:[0,1]
	v_pk_mul_f32 v[48:49], v[114:115], v[48:49] op_sel_hi:[0,1]
	v_pk_fma_f32 v[0:1], v[112:113], v[126:127], v[0:1] op_sel_hi:[0,1,1]
	v_pk_fma_f32 v[10:11], v[112:113], v[10:11], v[16:17] op_sel_hi:[0,1,1]
	v_pk_fma_f32 v[16:17], v[112:113], v[30:31], v[24:25] op_sel_hi:[0,1,1]
	v_pk_fma_f32 v[24:25], v[112:113], v[42:43], v[48:49] op_sel_hi:[0,1,1]
	v_mov_b32_e32 v113, v114
	v_pk_fma_f32 v[12:13], v[116:117], v[62:63], v[12:13] op_sel_hi:[0,1,1]
	v_pk_fma_f32 v[6:7], v[116:117], v[6:7], v[20:21] op_sel_hi:[0,1,1]
	v_pk_fma_f32 v[20:21], v[116:117], v[38:39], v[32:33] op_sel_hi:[0,1,1]
	v_pk_fma_f32 v[32:33], v[116:117], v[46:47], v[56:57] op_sel_hi:[0,1,1]
	v_mov_b32_e32 v117, v118
	s_waitcnt vmcnt(25)
	v_pk_fma_f32 v[0:1], v[124:125], v[8:9], v[0:1] op_sel_hi:[0,1,1]
	v_pk_fma_f32 v[8:9], v[124:125], v[28:29], v[10:11] op_sel_hi:[0,1,1]
	v_pk_fma_f32 v[10:11], v[124:125], v[40:41], v[16:17] op_sel_hi:[0,1,1]
	v_pk_fma_f32 v[16:17], v[124:125], v[60:61], v[24:25] op_sel_hi:[0,1,1]
	s_waitcnt lgkmcnt(1)
	v_pk_mul_f32 v[24:25], v[112:113], v[52:53]
	s_waitcnt vmcnt(24)
	v_mov_b32_e32 v125, v100
	v_pk_fma_f32 v[4:5], v[120:121], v[4:5], v[12:13] op_sel_hi:[0,1,1]
	v_pk_fma_f32 v[6:7], v[120:121], v[36:37], v[6:7] op_sel_hi:[0,1,1]
	v_pk_fma_f32 v[12:13], v[120:121], v[44:45], v[20:21] op_sel_hi:[0,1,1]
	v_pk_fma_f32 v[20:21], v[120:121], v[64:65], v[32:33] op_sel_hi:[0,1,1]
	s_waitcnt lgkmcnt(0)
	v_pk_mul_f32 v[30:31], v[116:117], v[108:109]
	v_mov_b32_e32 v121, v122
	v_pk_fma_f32 v[0:1], v[100:101], v[2:3], v[0:1] op_sel_hi:[0,1,1]
	v_pk_fma_f32 v[2:3], v[100:101], v[18:19], v[8:9] op_sel_hi:[0,1,1]
	v_pk_fma_f32 v[8:9], v[100:101], v[26:27], v[10:11] op_sel_hi:[0,1,1]
	v_pk_fma_f32 v[10:11], v[100:101], v[50:51], v[16:17] op_sel_hi:[0,1,1]
	v_pk_mul_f32 v[16:17], v[124:125], v[54:55]
	v_add_f32_e32 v18, v24, v25
	v_pk_fma_f32 v[4:5], v[122:123], v[14:15], v[4:5] op_sel_hi:[0,1,1]
	v_pk_fma_f32 v[6:7], v[122:123], v[22:23], v[6:7] op_sel_hi:[0,1,1]
	v_pk_fma_f32 v[14:15], v[122:123], v[58:59], v[20:21] op_sel_hi:[0,1,1]
	v_pk_mul_f32 v[20:21], v[120:121], v[110:111]
	v_add_f32_e32 v22, v30, v31
	v_add_f32_e32 v16, v18, v16
	v_add_f32_e32 v19, v22, v20
	v_pk_add_f32 v[0:1], v[96:97], v[0:1]
	v_add_f32_e32 v16, v16, v17
	v_pk_fma_f32 v[12:13], v[122:123], v[34:35], v[12:13] op_sel_hi:[0,1,1]
	v_pk_add_f32 v[2:3], v[94:95], v[2:3]
	v_pk_add_f32 v[8:9], v[92:93], v[8:9]
	v_pk_add_f32 v[10:11], v[90:91], v[10:11]
	v_add_f32_e32 v18, v19, v21
	v_pk_add_f32 v[96:97], v[0:1], v[4:5]
	v_add_f32_e32 v0, v105, v16
	v_pk_add_f32 v[94:95], v[2:3], v[6:7]
	v_pk_add_f32 v[92:93], v[8:9], v[12:13]
	v_pk_add_f32 v[90:91], v[10:11], v[14:15]
	v_add_f32_e32 v105, v0, v18
	ds_read_b128 v[8:11], v106 offset:32
	ds_read_b128 v[4:7], v106 offset:48
	ds_read_b128 v[0:3], v106 offset:4128
	ds_read_b128 v[12:15], v106 offset:4144
	ds_read_b128 v[28:31], v106 offset:8224
	ds_read_b128 v[36:39], v106 offset:8240
	ds_read_b128 v[16:19], v106 offset:12320
	ds_read_b128 v[20:23], v106 offset:12336
	ds_read_b128 v[40:43], v106 offset:16416
	ds_read_b128 v[44:47], v106 offset:16432
	ds_read_b128 v[24:27], v106 offset:20512
	ds_read_b128 v[32:35], v106 offset:20528
	ds_read_b128 v[60:63], v106 offset:24608
	ds_read_b128 v[64:67], v106 offset:24624
	ds_read_b128 v[48:51], v106 offset:28704
	ds_read_b128 v[56:59], v106 offset:28720
	ds_read_b128 v[52:55], v106 offset:32800
	ds_read_b128 v[108:111], v106 offset:32816
	s_waitcnt lgkmcnt(14)
	v_mov_b32_e32 v127, v0
	v_mov_b32_e32 v0, v9
	v_mov_b32_e32 v9, v2
	v_mov_b32_e32 v2, v11
	s_waitcnt lgkmcnt(11)
	v_mov_b32_e32 v11, v16
	v_mov_b32_e32 v16, v29
	v_mov_b32_e32 v29, v18
	v_mov_b32_e32 v18, v31
	s_waitcnt lgkmcnt(7)
	v_mov_b32_e32 v31, v24
	v_mov_b32_e32 v24, v41
	v_mov_b32_e32 v41, v26
	v_mov_b32_e32 v26, v43
	s_waitcnt lgkmcnt(3)
	v_mov_b32_e32 v43, v48
	v_mov_b32_e32 v48, v61
	v_mov_b32_e32 v126, v8
	v_mov_b32_e32 v8, v10
	v_mov_b32_e32 v10, v28
	v_mov_b32_e32 v28, v30
	v_mov_b32_e32 v30, v40
	v_mov_b32_e32 v40, v42
	v_mov_b32_e32 v42, v60
	v_mov_b32_e32 v61, v50
	v_mov_b32_e32 v50, v63
	v_mov_b32_e32 v63, v12
	v_mov_b32_e32 v12, v5
	v_mov_b32_e32 v5, v14
	v_mov_b32_e32 v14, v7
	v_mov_b32_e32 v7, v20
	v_mov_b32_e32 v20, v37
	v_mov_b32_e32 v37, v22
	v_mov_b32_e32 v22, v39
	v_mov_b32_e32 v39, v32
	v_mov_b32_e32 v32, v45
	v_mov_b32_e32 v45, v34
	v_mov_b32_e32 v34, v47
	s_waitcnt lgkmcnt(2)
	v_mov_b32_e32 v47, v56
	v_mov_b32_e32 v56, v65
	v_mov_b32_e32 v60, v62
	v_mov_b32_e32 v62, v4
	v_mov_b32_e32 v4, v6
	v_mov_b32_e32 v6, v36
	v_mov_b32_e32 v36, v38
	v_mov_b32_e32 v38, v44
	v_mov_b32_e32 v44, v46
	v_mov_b32_e32 v46, v64
	v_mov_b32_e32 v64, v66
	v_mov_b32_e32 v65, v58
	v_mov_b32_e32 v58, v67
	s_waitcnt vmcnt(22)
	v_pk_mul_f32 v[12:13], v[134:135], v[12:13] op_sel_hi:[0,1]
	v_pk_mul_f32 v[20:21], v[134:135], v[20:21] op_sel_hi:[0,1]
	v_pk_mul_f32 v[32:33], v[134:135], v[32:33] op_sel_hi:[0,1]
	v_pk_mul_f32 v[56:57], v[134:135], v[56:57] op_sel_hi:[0,1]
	s_waitcnt vmcnt(18)
	v_pk_mul_f32 v[0:1], v[130:131], v[0:1] op_sel_hi:[0,1]
	v_pk_mul_f32 v[16:17], v[130:131], v[16:17] op_sel_hi:[0,1]
	v_pk_mul_f32 v[24:25], v[130:131], v[24:25] op_sel_hi:[0,1]
	v_pk_mul_f32 v[48:49], v[130:131], v[48:49] op_sel_hi:[0,1]
	v_pk_fma_f32 v[0:1], v[128:129], v[126:127], v[0:1] op_sel_hi:[0,1,1]
	v_pk_fma_f32 v[10:11], v[128:129], v[10:11], v[16:17] op_sel_hi:[0,1,1]
	v_pk_fma_f32 v[16:17], v[128:129], v[30:31], v[24:25] op_sel_hi:[0,1,1]
	v_pk_fma_f32 v[24:25], v[128:129], v[42:43], v[48:49] op_sel_hi:[0,1,1]
	v_mov_b32_e32 v129, v130
	v_pk_fma_f32 v[12:13], v[132:133], v[62:63], v[12:13] op_sel_hi:[0,1,1]
	v_pk_fma_f32 v[6:7], v[132:133], v[6:7], v[20:21] op_sel_hi:[0,1,1]
	v_pk_fma_f32 v[20:21], v[132:133], v[38:39], v[32:33] op_sel_hi:[0,1,1]
	v_pk_fma_f32 v[32:33], v[132:133], v[46:47], v[56:57] op_sel_hi:[0,1,1]
	v_mov_b32_e32 v133, v134
	s_waitcnt vmcnt(17)
	v_pk_fma_f32 v[0:1], v[140:141], v[8:9], v[0:1] op_sel_hi:[0,1,1]
	v_pk_fma_f32 v[8:9], v[140:141], v[28:29], v[10:11] op_sel_hi:[0,1,1]
	v_pk_fma_f32 v[10:11], v[140:141], v[40:41], v[16:17] op_sel_hi:[0,1,1]
	v_pk_fma_f32 v[16:17], v[140:141], v[60:61], v[24:25] op_sel_hi:[0,1,1]
	s_waitcnt lgkmcnt(1)
	v_pk_mul_f32 v[24:25], v[128:129], v[52:53]
	s_waitcnt vmcnt(16)
	v_mov_b32_e32 v141, v142
	v_pk_fma_f32 v[4:5], v[136:137], v[4:5], v[12:13] op_sel_hi:[0,1,1]
	v_pk_fma_f32 v[6:7], v[136:137], v[36:37], v[6:7] op_sel_hi:[0,1,1]
	v_pk_fma_f32 v[12:13], v[136:137], v[44:45], v[20:21] op_sel_hi:[0,1,1]
	v_pk_fma_f32 v[20:21], v[136:137], v[64:65], v[32:33] op_sel_hi:[0,1,1]
	s_waitcnt lgkmcnt(0)
	v_pk_mul_f32 v[30:31], v[132:133], v[108:109]
	v_mov_b32_e32 v137, v138
	v_pk_fma_f32 v[0:1], v[142:143], v[2:3], v[0:1] op_sel_hi:[0,1,1]
	v_pk_fma_f32 v[2:3], v[142:143], v[18:19], v[8:9] op_sel_hi:[0,1,1]
	v_pk_fma_f32 v[8:9], v[142:143], v[26:27], v[10:11] op_sel_hi:[0,1,1]
	v_pk_fma_f32 v[10:11], v[142:143], v[50:51], v[16:17] op_sel_hi:[0,1,1]
	v_pk_mul_f32 v[16:17], v[140:141], v[54:55]
	v_add_f32_e32 v18, v24, v25
	v_pk_fma_f32 v[4:5], v[138:139], v[14:15], v[4:5] op_sel_hi:[0,1,1]
	v_pk_fma_f32 v[6:7], v[138:139], v[22:23], v[6:7] op_sel_hi:[0,1,1]
	v_pk_fma_f32 v[14:15], v[138:139], v[58:59], v[20:21] op_sel_hi:[0,1,1]
	v_pk_mul_f32 v[20:21], v[136:137], v[110:111]
	v_add_f32_e32 v22, v30, v31
	v_add_f32_e32 v16, v18, v16
	v_add_f32_e32 v19, v22, v20
	v_pk_add_f32 v[0:1], v[96:97], v[0:1]
	v_add_f32_e32 v16, v16, v17
	v_pk_fma_f32 v[12:13], v[138:139], v[34:35], v[12:13] op_sel_hi:[0,1,1]
	v_pk_add_f32 v[2:3], v[94:95], v[2:3]
	v_pk_add_f32 v[8:9], v[92:93], v[8:9]
	v_pk_add_f32 v[10:11], v[90:91], v[10:11]
	v_add_f32_e32 v18, v19, v21
	v_pk_add_f32 v[96:97], v[0:1], v[4:5]
	v_add_f32_e32 v0, v105, v16
	v_pk_add_f32 v[94:95], v[2:3], v[6:7]
	v_pk_add_f32 v[92:93], v[8:9], v[12:13]
	v_pk_add_f32 v[90:91], v[10:11], v[14:15]
	v_add_f32_e32 v105, v0, v18
	ds_read_b128 v[8:11], v106 offset:64
	ds_read_b128 v[4:7], v106 offset:80
	ds_read_b128 v[0:3], v106 offset:4160
	ds_read_b128 v[12:15], v106 offset:4176
	ds_read_b128 v[28:31], v106 offset:8256
	ds_read_b128 v[36:39], v106 offset:8272
	ds_read_b128 v[16:19], v106 offset:12352
	ds_read_b128 v[20:23], v106 offset:12368
	ds_read_b128 v[40:43], v106 offset:16448
	ds_read_b128 v[44:47], v106 offset:16464
	ds_read_b128 v[24:27], v106 offset:20544
	ds_read_b128 v[32:35], v106 offset:20560
	ds_read_b128 v[60:63], v106 offset:24640
	ds_read_b128 v[64:67], v106 offset:24656
	ds_read_b128 v[48:51], v106 offset:28736
	ds_read_b128 v[56:59], v106 offset:28752
	ds_read_b128 v[52:55], v106 offset:32832
	ds_read_b128 v[108:111], v106 offset:32848
	s_waitcnt lgkmcnt(14)
	v_mov_b32_e32 v127, v0
	v_mov_b32_e32 v0, v9
	v_mov_b32_e32 v9, v2
	v_mov_b32_e32 v2, v11
	s_waitcnt lgkmcnt(11)
	v_mov_b32_e32 v11, v16
	v_mov_b32_e32 v16, v29
	v_mov_b32_e32 v29, v18
	v_mov_b32_e32 v18, v31
	s_waitcnt lgkmcnt(7)
	v_mov_b32_e32 v31, v24
	v_mov_b32_e32 v24, v41
	v_mov_b32_e32 v41, v26
	v_mov_b32_e32 v26, v43
	s_waitcnt lgkmcnt(3)
	v_mov_b32_e32 v43, v48
	v_mov_b32_e32 v48, v61
	v_mov_b32_e32 v126, v8
	v_mov_b32_e32 v8, v10
	v_mov_b32_e32 v10, v28
	v_mov_b32_e32 v28, v30
	v_mov_b32_e32 v30, v40
	v_mov_b32_e32 v40, v42
	v_mov_b32_e32 v42, v60
	v_mov_b32_e32 v61, v50
	v_mov_b32_e32 v50, v63
	v_mov_b32_e32 v63, v12
	v_mov_b32_e32 v12, v5
	v_mov_b32_e32 v5, v14
	v_mov_b32_e32 v14, v7
	v_mov_b32_e32 v7, v20
	v_mov_b32_e32 v20, v37
	v_mov_b32_e32 v37, v22
	v_mov_b32_e32 v22, v39
	v_mov_b32_e32 v39, v32
	v_mov_b32_e32 v32, v45
	v_mov_b32_e32 v45, v34
	v_mov_b32_e32 v34, v47
	s_waitcnt lgkmcnt(2)
	v_mov_b32_e32 v47, v56
	v_mov_b32_e32 v56, v65
	v_mov_b32_e32 v60, v62
	v_mov_b32_e32 v62, v4
	v_mov_b32_e32 v4, v6
	v_mov_b32_e32 v6, v36
	v_mov_b32_e32 v36, v38
	v_mov_b32_e32 v38, v44
	v_mov_b32_e32 v44, v46
	v_mov_b32_e32 v46, v64
	v_mov_b32_e32 v64, v66
	v_mov_b32_e32 v65, v58
	v_mov_b32_e32 v58, v67
	s_waitcnt vmcnt(14)
	v_pk_mul_f32 v[12:13], v[150:151], v[12:13] op_sel_hi:[0,1]
	v_pk_mul_f32 v[20:21], v[150:151], v[20:21] op_sel_hi:[0,1]
	v_pk_mul_f32 v[32:33], v[150:151], v[32:33] op_sel_hi:[0,1]
	v_pk_mul_f32 v[56:57], v[150:151], v[56:57] op_sel_hi:[0,1]
	s_waitcnt vmcnt(10)
	v_pk_mul_f32 v[0:1], v[146:147], v[0:1] op_sel_hi:[0,1]
	v_pk_mul_f32 v[16:17], v[146:147], v[16:17] op_sel_hi:[0,1]
	v_pk_mul_f32 v[24:25], v[146:147], v[24:25] op_sel_hi:[0,1]
	v_pk_mul_f32 v[48:49], v[146:147], v[48:49] op_sel_hi:[0,1]
	v_pk_fma_f32 v[0:1], v[144:145], v[126:127], v[0:1] op_sel_hi:[0,1,1]
	v_pk_fma_f32 v[10:11], v[144:145], v[10:11], v[16:17] op_sel_hi:[0,1,1]
	v_pk_fma_f32 v[16:17], v[144:145], v[30:31], v[24:25] op_sel_hi:[0,1,1]
	v_pk_fma_f32 v[24:25], v[144:145], v[42:43], v[48:49] op_sel_hi:[0,1,1]
	v_mov_b32_e32 v145, v146
	v_pk_fma_f32 v[12:13], v[148:149], v[62:63], v[12:13] op_sel_hi:[0,1,1]
	v_pk_fma_f32 v[6:7], v[148:149], v[6:7], v[20:21] op_sel_hi:[0,1,1]
	v_pk_fma_f32 v[20:21], v[148:149], v[38:39], v[32:33] op_sel_hi:[0,1,1]
	v_pk_fma_f32 v[32:33], v[148:149], v[46:47], v[56:57] op_sel_hi:[0,1,1]
	v_mov_b32_e32 v149, v150
	s_waitcnt vmcnt(9)
	v_pk_fma_f32 v[0:1], v[156:157], v[8:9], v[0:1] op_sel_hi:[0,1,1]
	v_pk_fma_f32 v[8:9], v[156:157], v[28:29], v[10:11] op_sel_hi:[0,1,1]
	v_pk_fma_f32 v[10:11], v[156:157], v[40:41], v[16:17] op_sel_hi:[0,1,1]
	v_pk_fma_f32 v[16:17], v[156:157], v[60:61], v[24:25] op_sel_hi:[0,1,1]
	s_waitcnt lgkmcnt(1)
	v_pk_mul_f32 v[24:25], v[144:145], v[52:53]
	s_waitcnt vmcnt(8)
	v_mov_b32_e32 v157, v158
	v_pk_fma_f32 v[4:5], v[152:153], v[4:5], v[12:13] op_sel_hi:[0,1,1]
	v_pk_fma_f32 v[6:7], v[152:153], v[36:37], v[6:7] op_sel_hi:[0,1,1]
	v_pk_fma_f32 v[12:13], v[152:153], v[44:45], v[20:21] op_sel_hi:[0,1,1]
	v_pk_fma_f32 v[20:21], v[152:153], v[64:65], v[32:33] op_sel_hi:[0,1,1]
	s_waitcnt lgkmcnt(0)
	v_pk_mul_f32 v[30:31], v[148:149], v[108:109]
	v_mov_b32_e32 v153, v154
	v_pk_fma_f32 v[0:1], v[158:159], v[2:3], v[0:1] op_sel_hi:[0,1,1]
	v_pk_fma_f32 v[2:3], v[158:159], v[18:19], v[8:9] op_sel_hi:[0,1,1]
	v_pk_fma_f32 v[8:9], v[158:159], v[26:27], v[10:11] op_sel_hi:[0,1,1]
	v_pk_fma_f32 v[10:11], v[158:159], v[50:51], v[16:17] op_sel_hi:[0,1,1]
	v_pk_mul_f32 v[16:17], v[156:157], v[54:55]
	v_add_f32_e32 v18, v24, v25
	v_pk_fma_f32 v[4:5], v[154:155], v[14:15], v[4:5] op_sel_hi:[0,1,1]
	v_pk_fma_f32 v[6:7], v[154:155], v[22:23], v[6:7] op_sel_hi:[0,1,1]
	v_pk_fma_f32 v[14:15], v[154:155], v[58:59], v[20:21] op_sel_hi:[0,1,1]
	v_pk_mul_f32 v[20:21], v[152:153], v[110:111]
	v_add_f32_e32 v22, v30, v31
	v_add_f32_e32 v16, v18, v16
	v_add_f32_e32 v19, v22, v20
	v_pk_add_f32 v[0:1], v[96:97], v[0:1]
	v_add_f32_e32 v16, v16, v17
	v_pk_fma_f32 v[12:13], v[154:155], v[34:35], v[12:13] op_sel_hi:[0,1,1]
	v_pk_add_f32 v[2:3], v[94:95], v[2:3]
	v_pk_add_f32 v[8:9], v[92:93], v[8:9]
	v_pk_add_f32 v[10:11], v[90:91], v[10:11]
	v_add_f32_e32 v18, v19, v21
	v_pk_add_f32 v[96:97], v[0:1], v[4:5]
	v_add_f32_e32 v0, v105, v16
	v_pk_add_f32 v[94:95], v[2:3], v[6:7]
	v_pk_add_f32 v[92:93], v[8:9], v[12:13]
	v_pk_add_f32 v[90:91], v[10:11], v[14:15]
	v_add_f32_e32 v105, v0, v18
	ds_read_b128 v[8:11], v106 offset:96
	ds_read_b128 v[4:7], v106 offset:112
	ds_read_b128 v[0:3], v106 offset:4192
	ds_read_b128 v[12:15], v106 offset:4208
	ds_read_b128 v[28:31], v106 offset:8288
	ds_read_b128 v[36:39], v106 offset:8304
	ds_read_b128 v[16:19], v106 offset:12384
	ds_read_b128 v[20:23], v106 offset:12400
	ds_read_b128 v[40:43], v106 offset:16480
	ds_read_b128 v[44:47], v106 offset:16496
	ds_read_b128 v[24:27], v106 offset:20576
	ds_read_b128 v[32:35], v106 offset:20592
	ds_read_b128 v[60:63], v106 offset:24672
	ds_read_b128 v[64:67], v106 offset:24688
	ds_read_b128 v[48:51], v106 offset:28768
	ds_read_b128 v[56:59], v106 offset:28784
	ds_read_b128 v[52:55], v106 offset:32864
	ds_read_b128 v[108:111], v106 offset:32880
	s_waitcnt lgkmcnt(14)
	v_mov_b32_e32 v127, v0
	v_mov_b32_e32 v0, v9
	v_mov_b32_e32 v9, v2
	v_mov_b32_e32 v2, v11
	s_waitcnt lgkmcnt(11)
	v_mov_b32_e32 v11, v16
	v_mov_b32_e32 v16, v29
	v_mov_b32_e32 v29, v18
	v_mov_b32_e32 v18, v31
	s_waitcnt lgkmcnt(7)
	v_mov_b32_e32 v31, v24
	v_mov_b32_e32 v24, v41
	v_mov_b32_e32 v41, v26
	v_mov_b32_e32 v26, v43
	s_waitcnt lgkmcnt(3)
	v_mov_b32_e32 v43, v48
	v_mov_b32_e32 v48, v61
	v_mov_b32_e32 v126, v8
	v_mov_b32_e32 v8, v10
	v_mov_b32_e32 v10, v28
	v_mov_b32_e32 v28, v30
	v_mov_b32_e32 v30, v40
	v_mov_b32_e32 v40, v42
	v_mov_b32_e32 v42, v60
	v_mov_b32_e32 v61, v50
	v_mov_b32_e32 v50, v63
	v_mov_b32_e32 v63, v12
	v_mov_b32_e32 v12, v5
	v_mov_b32_e32 v5, v14
	v_mov_b32_e32 v14, v7
	v_mov_b32_e32 v7, v20
	v_mov_b32_e32 v20, v37
	v_mov_b32_e32 v37, v22
	v_mov_b32_e32 v22, v39
	v_mov_b32_e32 v39, v32
	v_mov_b32_e32 v32, v45
	v_mov_b32_e32 v45, v34
	v_mov_b32_e32 v34, v47
	s_waitcnt lgkmcnt(2)
	v_mov_b32_e32 v47, v56
	v_mov_b32_e32 v56, v65
	v_mov_b32_e32 v60, v62
	v_mov_b32_e32 v62, v4
	v_mov_b32_e32 v4, v6
	v_mov_b32_e32 v6, v36
	v_mov_b32_e32 v36, v38
	v_mov_b32_e32 v38, v44
	v_mov_b32_e32 v44, v46
	v_mov_b32_e32 v46, v64
	v_mov_b32_e32 v64, v66
	v_mov_b32_e32 v65, v58
	v_mov_b32_e32 v58, v67
	s_waitcnt vmcnt(6)
	v_pk_mul_f32 v[12:13], v[166:167], v[12:13] op_sel_hi:[0,1]
	v_pk_mul_f32 v[20:21], v[166:167], v[20:21] op_sel_hi:[0,1]
	v_pk_mul_f32 v[32:33], v[166:167], v[32:33] op_sel_hi:[0,1]
	v_pk_mul_f32 v[56:57], v[166:167], v[56:57] op_sel_hi:[0,1]
	s_waitcnt vmcnt(2)
	v_pk_mul_f32 v[0:1], v[162:163], v[0:1] op_sel_hi:[0,1]
	v_pk_mul_f32 v[16:17], v[162:163], v[16:17] op_sel_hi:[0,1]
	v_pk_mul_f32 v[24:25], v[162:163], v[24:25] op_sel_hi:[0,1]
	v_pk_mul_f32 v[48:49], v[162:163], v[48:49] op_sel_hi:[0,1]
	v_pk_fma_f32 v[0:1], v[160:161], v[126:127], v[0:1] op_sel_hi:[0,1,1]
	v_pk_fma_f32 v[10:11], v[160:161], v[10:11], v[16:17] op_sel_hi:[0,1,1]
	v_pk_fma_f32 v[16:17], v[160:161], v[30:31], v[24:25] op_sel_hi:[0,1,1]
	v_pk_fma_f32 v[24:25], v[160:161], v[42:43], v[48:49] op_sel_hi:[0,1,1]
	v_mov_b32_e32 v161, v162
	v_pk_fma_f32 v[12:13], v[164:165], v[62:63], v[12:13] op_sel_hi:[0,1,1]
	v_pk_fma_f32 v[6:7], v[164:165], v[6:7], v[20:21] op_sel_hi:[0,1,1]
	v_pk_fma_f32 v[20:21], v[164:165], v[38:39], v[32:33] op_sel_hi:[0,1,1]
	v_pk_fma_f32 v[32:33], v[164:165], v[46:47], v[56:57] op_sel_hi:[0,1,1]
	v_mov_b32_e32 v165, v166
	s_waitcnt vmcnt(1)
	v_pk_fma_f32 v[0:1], v[172:173], v[8:9], v[0:1] op_sel_hi:[0,1,1]
	v_pk_fma_f32 v[8:9], v[172:173], v[28:29], v[10:11] op_sel_hi:[0,1,1]
	v_pk_fma_f32 v[10:11], v[172:173], v[40:41], v[16:17] op_sel_hi:[0,1,1]
	v_pk_fma_f32 v[16:17], v[172:173], v[60:61], v[24:25] op_sel_hi:[0,1,1]
	s_waitcnt lgkmcnt(1)
	v_pk_mul_f32 v[24:25], v[160:161], v[52:53]
	s_waitcnt vmcnt(0)
	v_mov_b32_e32 v173, v174
	v_pk_fma_f32 v[4:5], v[168:169], v[4:5], v[12:13] op_sel_hi:[0,1,1]
	v_pk_fma_f32 v[6:7], v[168:169], v[36:37], v[6:7] op_sel_hi:[0,1,1]
	v_pk_fma_f32 v[12:13], v[168:169], v[44:45], v[20:21] op_sel_hi:[0,1,1]
	v_pk_fma_f32 v[20:21], v[168:169], v[64:65], v[32:33] op_sel_hi:[0,1,1]
	s_waitcnt lgkmcnt(0)
	v_pk_mul_f32 v[30:31], v[164:165], v[108:109]
	v_mov_b32_e32 v169, v170
	v_pk_fma_f32 v[0:1], v[174:175], v[2:3], v[0:1] op_sel_hi:[0,1,1]
	v_pk_fma_f32 v[2:3], v[174:175], v[18:19], v[8:9] op_sel_hi:[0,1,1]
	v_pk_fma_f32 v[8:9], v[174:175], v[26:27], v[10:11] op_sel_hi:[0,1,1]
	v_pk_fma_f32 v[10:11], v[174:175], v[50:51], v[16:17] op_sel_hi:[0,1,1]
	v_pk_mul_f32 v[16:17], v[172:173], v[54:55]
	v_add_f32_e32 v18, v24, v25
	v_pk_fma_f32 v[4:5], v[170:171], v[14:15], v[4:5] op_sel_hi:[0,1,1]
	v_pk_fma_f32 v[6:7], v[170:171], v[22:23], v[6:7] op_sel_hi:[0,1,1]
	v_pk_fma_f32 v[14:15], v[170:171], v[58:59], v[20:21] op_sel_hi:[0,1,1]
	v_pk_mul_f32 v[20:21], v[168:169], v[110:111]
	v_add_f32_e32 v22, v30, v31
	v_add_f32_e32 v16, v18, v16
	v_add_f32_e32 v19, v22, v20
	v_pk_add_f32 v[0:1], v[96:97], v[0:1]
	v_add_f32_e32 v16, v16, v17
	v_pk_fma_f32 v[12:13], v[170:171], v[34:35], v[12:13] op_sel_hi:[0,1,1]
	v_pk_add_f32 v[2:3], v[94:95], v[2:3]
	v_pk_add_f32 v[8:9], v[92:93], v[8:9]
	v_pk_add_f32 v[10:11], v[90:91], v[10:11]
	v_add_f32_e32 v18, v19, v21
	v_pk_add_f32 v[96:97], v[0:1], v[4:5]
	v_add_f32_e32 v0, v105, v16
	v_pk_add_f32 v[94:95], v[2:3], v[6:7]
	v_pk_add_f32 v[92:93], v[8:9], v[12:13]
	v_pk_add_f32 v[90:91], v[10:11], v[14:15]
	v_add_f32_e32 v105, v0, v18
	s_add_u32 s62, s62, 0xc0000
	s_addc_u32 s63, s63, 0
	v_add_u32_e32 v106, 0x80, v106
	s_cmp_eq_u32 s62, 0x600000
	s_cbranch_scc0 .LBB0_1340
	s_add_i32 s31, s31, 1
	s_mov_b64 s[0:1], 0x600000
	s_cmp_eq_u32 s31, 4
	v_lshl_add_u64 v[98:99], v[98:99], 0, s[0:1]
	s_cbranch_scc0 .LBB0_1319
	s_mul_i32 s0, s30, 0x1800
	s_add_i32 s0, s0, s60
	v_or_b32_e32 v0, s0, v68
	v_ashrrev_i32_e32 v1, 31, v0
	v_lshl_add_u64 v[0:1], v[0:1], 2, s[82:83]
	global_load_dword v2, v[0:1], off
	s_mul_hi_i32 s59, s30, 33
	s_mul_i32 s58, s30, 33
	v_lshl_add_u64 v[0:1], s[60:61], 2, v[88:89]
	s_and_b64 s[0:1], s[40:41], s[34:35]
	s_and_saveexec_b64 s[20:21], s[0:1]
	s_cbranch_execnz .LBB0_1352
	s_or_b64 exec, exec, s[20:21]
	s_and_b64 s[0:1], s[42:43], s[34:35]
	s_and_saveexec_b64 s[20:21], s[0:1]
	s_cbranch_execnz .LBB0_1353
